# half of the workgroups run QKV(g+1) before attention(g) so bandwidth-bound and MFMA-bound work overlap; snake MFMA order
# baseline (speedup 1.0000x reference)
; __global__ void __launch_bounds__(NTHREADS, 2) fwd_megakernel(Args a) {
;     ...
;         switch (step) {
;             case 0: kind = 0; break;
;             case 1: kind = 1; p0 = 0; break;
;             case 2: kind = 2; p0 = 0; break;
;             case 3: kind = 3; break;
;             case 4: kind = 4; break;
;             case 5: kind = 2; p0 = 4; break;
;             case 6: kind = 1; p0 = 1; break;
;             case 7: kind = 2; p0 = 1; break;
;             case 8: kind = 1; p0 = 2; break;
;             case 9: kind = 2; p0 = 2; break;
;             case 10: kind = 5; p0 = 0; break;
;             case 11: kind = 6; p0 = 0; break;
;             case 12: kind = 5; p0 = 1; break;
;             case 13: kind = 6; p0 = 1; break;
;             case 14: kind = 5; p0 = 2; break;
;             case 15: kind = 6; p0 = 2; break;
;             case 16: kind = 2; p0 = 5; break;
;             case 17: kind = 1; p0 = 3; break;
;             default: kind = 2; p0 = 3; break;
;         }
.LBB0_14:
	v_readlane_b32 s0, v254, 21
	s_nop 1
	s_bitcmp1_b32 s0, 3
	s_cbranch_scc0 .Lsw_skip_a
	s_sub_i32 s0, s38, 11
	s_cmp_lt_u32 s0, 4
	s_cbranch_scc0 .Lsw_skip_a
	s_xor_b32 s0, s0, 1
	s_add_i32 s38, s0, 11

; __global__ void __launch_bounds__(NTHREADS, 2) fwd_megakernel(Args a) {
;     ...
;         switch (step) {
;             case 0: kind = 0; break;
;             case 1: kind = 1; p0 = 0; break;
;             case 2: kind = 2; p0 = 0; break;
;             case 3: kind = 3; break;
;             case 4: kind = 4; break;
;             case 5: kind = 2; p0 = 4; break;
;             case 6: kind = 1; p0 = 1; break;
;             case 7: kind = 2; p0 = 1; break;
;             case 8: kind = 1; p0 = 2; break;
;             case 9: kind = 2; p0 = 2; break;
;             case 10: kind = 5; p0 = 0; break;
;             case 11: kind = 6; p0 = 0; break;
;             case 12: kind = 5; p0 = 1; break;
;             case 13: kind = 6; p0 = 1; break;
;             case 14: kind = 5; p0 = 2; break;
;             case 15: kind = 6; p0 = 2; break;
;             case 16: kind = 2; p0 = 5; break;
;             case 17: kind = 1; p0 = 3; break;
;             default: kind = 2; p0 = 3; break;
;         }
.LBB0_552:
	v_readlane_b32 s0, v254, 21
	s_nop 1
	s_bitcmp1_b32 s0, 3
	s_cbranch_scc0 .Lsw_skip_b
	s_sub_i32 s0, s31, 11
	s_cmp_lt_u32 s0, 4
	s_cbranch_scc0 .Lsw_skip_b
	s_xor_b32 s0, s0, 1
	s_add_i32 s31, s0, 11

; __global__ void __launch_bounds__(NTHREADS, 2) fwd_megakernel(Args a) {
;     ...
;     for (int step = a.step_lo; step < a.step_hi; ++step) {
;     ...
;         if (step + 1 < a.step_hi && step != 11 && step != 13) { if (a.step_hi > 1000) cg::this_grid().sync(); else xcd_barrier(bar); }
;     }
.LBB0_567:
	s_or_b64 exec, exec, s[0:1]
	v_readlane_b32 s0, v254, 21
	s_nop 1
	s_bitcmp1_b32 s0, 3
	s_cbranch_scc0 .Lsw_skip_c
	s_sub_i32 s0, s31, 11
	s_cmp_lt_u32 s0, 4
	s_cbranch_scc0 .Lsw_skip_c
	s_xor_b32 s0, s0, 1
	s_add_i32 s31, s0, 11
.Lsw_skip_c:
	s_add_i32 s38, s31, 1
	s_cmp_lt_i32 s38, s39
	s_mov_b64 s[0:1], -1
	s_cbranch_scc0 .LBB0_13
.LBB0_568:
	s_cmp_lt_i32 s31, 13
	s_cbranch_scc1 .LBB0_570
	s_cmp_lg_u32 s31, 13
	s_cselect_b64 s[0:1], -1, 0
	s_cbranch_execz .LBB0_571
	s_branch .LBB0_572
